# grid barrier: non-leader release poll keeps two loads in flight half a period apart
# speedup vs baseline: 1.0008x; 1.0008x over previous
.LBB0_1506:
	s_or_b64 exec, exec, s[12:13]
	s_waitcnt vmcnt(0)
	v_readfirstlane_b32 s2, v3
	v_sub_u32_e32 v4, 0, v2
	s_nop 0
	v_add_u32_e32 v3, s2, v1
	v_cvt_f32_u32_e32 v1, v2
	v_rcp_iflag_f32_e32 v1, v1
	s_nop 0
	v_mul_f32_e32 v1, 0x4f7ffffe, v1
	v_cvt_u32_f32_e32 v1, v1
	v_mul_lo_u32 v4, v4, v1
	v_mul_hi_u32 v4, v1, v4
	v_add_u32_e32 v1, v1, v4
	v_mul_hi_u32 v1, v3, v1
	v_mul_lo_u32 v4, v1, v2
	v_sub_u32_e32 v4, v3, v4
	v_cmp_ge_u32_e32 vcc, v4, v2
	v_add_u32_e32 v5, 1, v1
	s_nop 0
	v_cndmask_b32_e32 v1, v1, v5, vcc
	v_sub_u32_e32 v5, v4, v2
	v_cndmask_b32_e32 v4, v4, v5, vcc
	v_cmp_ge_u32_e32 vcc, v4, v2
	v_add_u32_e32 v4, 1, v1
	s_nop 0
	v_cndmask_b32_e32 v1, v1, v4, vcc
	v_add_u32_e32 v4, 1, v3
	v_mad_u64_u32 v[2:3], s[10:11], v2, v1, v[2:3]
	v_cmp_ne_u32_e32 vcc, v4, v2
	s_and_saveexec_b64 s[10:11], vcc
	s_xor_b64 s[10:11], exec, s[10:11]
	s_cbranch_execz .LBB0_1511
	buffer_inv sc1
	v_mov_b32_e32 v0, 0x2000
	global_load_dword v0, v0, s[8:9] offset:1024 sc1
	s_add_u32 s12, s8, 0x2400
	s_addc_u32 s13, s9, 0
	s_waitcnt vmcnt(0)
	v_cmp_eq_u32_e32 vcc, v0, v1
	s_and_saveexec_b64 s[14:15], vcc
	s_cbranch_execz .LBB0_1510
	global_load_dword v0, v153, s[12:13] sc1
.LBB0_1509:
	s_sleep 6
	global_load_dword v5, v153, s[12:13] sc1
	s_waitcnt vmcnt(1)
	v_cmp_ne_u32_e32 vcc, v0, v1
	s_cbranch_vccnz .Lxb_rel
	s_sleep 6
	global_load_dword v0, v153, s[12:13] sc1
	s_waitcnt vmcnt(1)
	v_cmp_ne_u32_e32 vcc, v5, v1
	s_cbranch_vccz .LBB0_1509
.Lxb_rel:
	s_waitcnt vmcnt(0)
.LBB0_1510:
	s_or_b64 exec, exec, s[14:15]
	s_waitcnt lgkmcnt(0)
	s_waitcnt vmcnt(0)
